# PN: next-row prefetch waited for at the latch (vmcnt counted past the row's stores) instead of three quarters into the row
# baseline (speedup 1.0000x reference)
; DI void phase_norm(const Params& p, int l, const float* xin, LAS unsigned char* lds, int G, int bid) {
;     ...
;     for (int row = gw; row < M; row += NGW) {
;         const int b = row / S;
;         f32x4 v[4]; float ss = 0.f;
; #pragma unroll
;         for (int j = 0; j < 4; ++j) v[j] = vn[j];
;         if (row + NGW < M) {
; #pragma unroll
;             for (int j = 0; j < 4; ++j) vn[j] = ((const f32x4*)(xin + (size_t)(row + NGW) * D) + lane)[64 * j]; }
.LBB0_139:
	s_or_b64 exec, exec, s[0:1]
	s_and_b64 s[0:1], exec, s[42:43]
	s_or_b64 s[48:49], s[0:1], s[48:49]
	v_mov_b32_e32 v178, v179
	v_lshl_add_u64 v[176:177], v[176:177], 0, s[98:99]
	v_lshl_add_u64 v[172:173], v[172:173], 0, s[100:101]
	v_lshl_add_u64 v[174:175], v[174:175], 0, s[8:9]
	s_waitcnt vmcnt(5)
	v_mov_b64_e32 v[158:159], v[130:131]
	v_mov_b64_e32 v[160:161], v[132:133]
	v_mov_b64_e32 v[154:155], v[134:135]
	v_mov_b64_e32 v[156:157], v[136:137]
	v_mov_b64_e32 v[150:151], v[138:139]
	v_mov_b64_e32 v[152:153], v[140:141]
	v_mov_b64_e32 v[146:147], v[142:143]
	v_mov_b64_e32 v[148:149], v[144:145]
	s_andn2_b64 exec, exec, s[48:49]
	s_cbranch_execz .LBB0_144

; DI void phase_norm(const Params& p, int l, const float* xin, LAS unsigned char* lds, int G, int bid) {
;     ...
; #pragma unroll
;         for (int j = 0; j < 4; ++j) ss += (v[j].x * v[j].x + v[j].y * v[j].y) + (v[j].z * v[j].z + v[j].w * v[j].w);
;         const float rstd = 1.0f / sqrtf(wave_sum(ss) * (1.f / D) + EPS);
.LBB0_142:
	s_or_b64 exec, exec, s[0:1]
	v_ashrrev_i32_e32 v0, 31, v178
	v_lshrrev_b32_e32 v0, 19, v0
	v_add_u32_e32 v0, v178, v0
	v_ashrrev_i32_e32 v178, 13, v0
	v_pk_mul_f32 v[186:187], v[158:159], v[158:159]
	v_pk_mul_f32 v[188:189], v[160:161], v[160:161]
	v_pk_fma_f32 v[186:187], v[154:155], v[154:155], v[186:187]
	v_pk_fma_f32 v[188:189], v[156:157], v[156:157], v[188:189]
	v_pk_fma_f32 v[186:187], v[150:151], v[150:151], v[186:187]
	v_pk_fma_f32 v[188:189], v[152:153], v[152:153], v[188:189]
	v_pk_fma_f32 v[186:187], v[146:147], v[146:147], v[186:187]
	v_pk_fma_f32 v[188:189], v[148:149], v[148:149], v[188:189]
	s_mov_b32 s0, 0xf800000
	v_lshl_add_u32 v178, v178, 12, v185
	ds_read_b128 v[222:225], v178
	ds_read_b128 v[226:229], v178 offset:16384
	ds_read_b128 v[230:233], v178 offset:1024
	ds_read_b128 v[234:237], v178 offset:17408
	ds_read_b128 v[238:241], v178 offset:2048
	ds_read_b128 v[242:245], v178 offset:18432
	v_pk_add_f32 v[186:187], v[186:187], v[188:189]
	s_nop 0
	v_add_f32_e32 v0, v186, v187
	v_lshl_add_u64 v[194:195], s[92:93], 0, v[172:173]
	s_nop 1
	v_add_f32_dpp v0, v0, v0 quad_perm:[1,0,3,2] row_mask:0xf bank_mask:0xf
	s_nop 1
	v_add_f32_dpp v0, v0, v0 quad_perm:[2,3,0,1] row_mask:0xf bank_mask:0xf
	s_nop 1
	v_add_f32_dpp v0, v0, v0 row_half_mirror row_mask:0xf bank_mask:0xf
	s_nop 1
	v_add_f32_dpp v0, v0, v0 row_mirror row_mask:0xf bank_mask:0xf
	s_nop 3
	v_readlane_b32 s17, v0, 0
	v_readlane_b32 s23, v0, 16
	v_readlane_b32 s28, v0, 32
	v_readlane_b32 s29, v0, 48
	s_nop 1
	v_mov_b32_e32 v0, s17
	v_mov_b32_e32 v186, s28
	v_add_f32_e32 v0, s23, v0
	v_add_f32_e32 v186, s29, v186
	v_add_f32_e32 v0, v0, v186
	v_fmamk_f32 v0, v0, 0x3a800000, v204
	v_cmp_gt_f32_e32 vcc, s0, v0
	v_mul_f32_e32 v186, 0x4f800000, v0
	s_nop 0
	v_cndmask_b32_e32 v0, v0, v186, vcc
	v_sqrt_f32_e32 v186, v0
	s_nop 0
	v_add_u32_e32 v187, -1, v186
	v_fma_f32 v188, -v187, v186, v0
	v_cmp_ge_f32_e64 s[0:1], 0, v188
	v_add_u32_e32 v188, 1, v186
	s_nop 0
	v_cndmask_b32_e64 v187, v186, v187, s[0:1]
	v_fma_f32 v186, -v188, v186, v0
	v_cmp_lt_f32_e64 s[0:1], 0, v186
	s_nop 1
	v_cndmask_b32_e64 v186, v187, v188, s[0:1]
	v_mul_f32_e32 v187, 0x37800000, v186
	v_cndmask_b32_e32 v186, v186, v187, vcc
	v_cmp_class_f32_e32 vcc, v0, v205
	s_nop 1
	v_cndmask_b32_e32 v0, v186, v0, vcc
	v_div_scale_f32 v186, s[0:1], v0, v0, 1.0
	v_rcp_f32_e32 v187, v186
	s_brev_b32 s0, 32
	v_fma_f32 v188, -v186, v187, 1.0
	v_fmac_f32_e32 v187, v188, v187
	v_div_scale_f32 v188, vcc, 1.0, v0, 1.0
	v_mul_f32_e32 v189, v188, v187
	v_fma_f32 v190, -v186, v189, v188
	v_fmac_f32_e32 v189, v190, v187
	v_fma_f32 v186, -v186, v189, v188
	v_div_fmas_f32 v186, v186, v187, v189
	v_div_fixup_f32 v0, v186, v0, 1.0


; #define LAS __attribute__((address_space(3)))
; DI void phase_norm(const Params& p, int l, const float* xin, LAS unsigned char* lds, int G, int bid) {
;     ...
;         for (int j = 0; j < 4; ++j) {
;             const int k = 256 * j + 4 * lane;
;             const f32x4 aa = *(const LAS f32x4*)(pa + b * 1024 + k), sh = *(const LAS f32x4*)(pb + b * 1024 + k);
;             const f32x4 h = (v[j] * rstd) * aa + sh;
; #pragma unroll
;             for (int e = 0; e < 4; ++e) { g0 += w0[j][e] * h[e]; g1 += w1[j][e] * h[e]; }
;             o8[64 * j] = (unsigned long long)cvt_pk_bf16(h.x, h.y) | ((unsigned long long)cvt_pk_bf16(h.z, h.w) << 32);
;         }
	v_pk_mul_f32 v[158:159], v[158:159], v[0:1] op_sel_hi:[1,0]
	v_pk_mul_f32 v[160:161], v[160:161], v[0:1] op_sel_hi:[1,0]
	v_pk_mul_f32 v[154:155], v[154:155], v[0:1] op_sel_hi:[1,0]
	v_pk_mul_f32 v[156:157], v[156:157], v[0:1] op_sel_hi:[1,0]
	s_waitcnt lgkmcnt(4)
	v_pk_fma_f32 v[158:159], v[222:223], v[158:159], v[226:227]
	v_pk_fma_f32 v[160:161], v[224:225], v[160:161], v[228:229]
	v_pk_fma_f32 v[186:187], v[14:15], v[158:159], 0 op_sel_hi:[1,0,0]
	v_pk_fma_f32 v[188:189], v[16:17], v[158:159], 0 op_sel_hi:[1,0,0]
	v_pk_fma_f32 v[186:187], v[6:7], v[158:159], v[186:187] op_sel:[0,1,0]
	v_pk_fma_f32 v[190:191], v[10:11], v[158:159], 0 op_sel_hi:[1,0,0]
	v_pk_fma_f32 v[192:193], v[12:13], v[158:159], 0 op_sel_hi:[1,0,0]
	v_pk_fma_f32 v[186:187], v[30:31], v[160:161], v[186:187] op_sel_hi:[1,0,1]
	v_pk_fma_f32 v[188:189], v[8:9], v[158:159], v[188:189] op_sel:[0,1,0]
	v_pk_fma_f32 v[192:193], v[4:5], v[158:159], v[192:193] op_sel:[0,1,0]
	v_pk_fma_f32 v[190:191], v[2:3], v[158:159], v[190:191] op_sel:[0,1,0]
	v_pk_fma_f32 v[198:199], v[22:23], v[160:161], v[186:187] op_sel:[0,1,0]
	v_cvt_pk_bf16_f32 v186, v158, v159
	v_add_co_u32_e32 v158, vcc, s0, v194
	v_cvt_pk_bf16_f32 v187, v160, v161
	s_nop 0
	v_addc_co_u32_e32 v159, vcc, 0, v195, vcc
	v_pk_fma_f32 v[188:189], v[32:33], v[160:161], v[188:189] op_sel_hi:[1,0,1]
	v_pk_fma_f32 v[190:191], v[26:27], v[160:161], v[190:191] op_sel_hi:[1,0,1]
	v_pk_fma_f32 v[192:193], v[28:29], v[160:161], v[192:193] op_sel_hi:[1,0,1]
	global_store_dwordx2 v[158:159], v[186:187], off
	v_pk_fma_f32 v[196:197], v[24:25], v[160:161], v[188:189] op_sel:[0,1,0]
	v_pk_fma_f32 v[200:201], v[20:21], v[160:161], v[192:193] op_sel:[0,1,0]
	v_pk_fma_f32 v[218:219], v[18:19], v[160:161], v[190:191] op_sel:[0,1,0]


; #define LAS __attribute__((address_space(3)))
; DI void phase_norm(const Params& p, int l, const float* xin, LAS unsigned char* lds, int G, int bid) {
;     ...
;         for (int j = 0; j < 4; ++j) {
;             const int k = 256 * j + 4 * lane;
;             const f32x4 aa = *(const LAS f32x4*)(pa + b * 1024 + k), sh = *(const LAS f32x4*)(pb + b * 1024 + k);
;             const f32x4 h = (v[j] * rstd) * aa + sh;
; #pragma unroll
;             for (int e = 0; e < 4; ++e) { g0 += w0[j][e] * h[e]; g1 += w1[j][e] * h[e]; }
;             o8[64 * j] = (unsigned long long)cvt_pk_bf16(h.x, h.y) | ((unsigned long long)cvt_pk_bf16(h.z, h.w) << 32);
;         }
	v_pk_mul_f32 v[150:151], v[150:151], v[0:1] op_sel_hi:[1,0]
	v_pk_mul_f32 v[152:153], v[152:153], v[0:1] op_sel_hi:[1,0]
	v_pk_mul_f32 v[146:147], v[146:147], v[0:1] op_sel_hi:[1,0]
	v_pk_mul_f32 v[148:149], v[148:149], v[0:1] op_sel_hi:[1,0]
	s_waitcnt lgkmcnt(2)
	v_pk_fma_f32 v[154:155], v[230:231], v[154:155], v[234:235]
	v_pk_fma_f32 v[156:157], v[232:233], v[156:157], v[236:237]
	s_waitcnt vmcnt(9)
	v_pk_fma_f32 v[160:161], v[94:95], v[154:155], v[198:199] op_sel_hi:[1,0,1]
	v_pk_fma_f32 v[186:187], v[96:97], v[154:155], v[196:197] op_sel_hi:[1,0,1]
	v_pk_fma_f32 v[188:189], v[90:91], v[154:155], v[218:219] op_sel_hi:[1,0,1]
	v_pk_fma_f32 v[190:191], v[92:93], v[154:155], v[200:201] op_sel_hi:[1,0,1]
	v_pk_fma_f32 v[186:187], v[88:89], v[154:155], v[186:187] op_sel:[0,1,0]
	v_pk_fma_f32 v[160:161], v[86:87], v[154:155], v[160:161] op_sel:[0,1,0]
	v_pk_fma_f32 v[190:191], v[84:85], v[154:155], v[190:191] op_sel:[0,1,0]
	v_pk_fma_f32 v[188:189], v[82:83], v[154:155], v[188:189] op_sel:[0,1,0]
	v_cvt_pk_bf16_f32 v154, v154, v155
	v_cvt_pk_bf16_f32 v155, v156, v157
	v_pk_fma_f32 v[160:161], v[34:35], v[156:157], v[160:161] op_sel_hi:[1,0,1]
	v_pk_fma_f32 v[186:187], v[36:37], v[156:157], v[186:187] op_sel_hi:[1,0,1]
	v_pk_fma_f32 v[188:189], v[46:47], v[156:157], v[188:189] op_sel_hi:[1,0,1]
	v_pk_fma_f32 v[190:191], v[48:49], v[156:157], v[190:191] op_sel_hi:[1,0,1]
	global_store_dwordx2 v[158:159], v[154:155], off offset:512
	v_pk_fma_f32 v[192:193], v[44:45], v[156:157], v[186:187] op_sel:[0,1,0]
	v_pk_fma_f32 v[160:161], v[42:43], v[156:157], v[160:161] op_sel:[0,1,0]
	v_pk_fma_f32 v[190:191], v[40:41], v[156:157], v[190:191] op_sel:[0,1,0]
	v_pk_fma_f32 v[194:195], v[38:39], v[156:157], v[188:189] op_sel:[0,1,0]


; #define LAS __attribute__((address_space(3)))
; DI void phase_norm(const Params& p, int l, const float* xin, LAS unsigned char* lds, int G, int bid) {
;     ...
;         for (int j = 0; j < 4; ++j) {
;             const int k = 256 * j + 4 * lane;
;             const f32x4 aa = *(const LAS f32x4*)(pa + b * 1024 + k), sh = *(const LAS f32x4*)(pb + b * 1024 + k);
;             const f32x4 h = (v[j] * rstd) * aa + sh;
; #pragma unroll
;             for (int e = 0; e < 4; ++e) { g0 += w0[j][e] * h[e]; g1 += w1[j][e] * h[e]; }
;             o8[64 * j] = (unsigned long long)cvt_pk_bf16(h.x, h.y) | ((unsigned long long)cvt_pk_bf16(h.z, h.w) << 32);
;         }
; #pragma unroll
;         for (int e = 0; e < 4; ++e) { g0[e] = wave_sum(g0[e]); g1[e] = wave_sum(g1[e]); }
;         if (lane == 0) { *(f32x4*)(gates + (size_t)row * 8) = g0; *(f32x4*)(gates + (size_t)row * 8 + 4) = g1; }
	s_waitcnt lgkmcnt(0)
	v_pk_fma_f32 v[150:151], v[238:239], v[150:151], v[242:243]
	v_pk_fma_f32 v[152:153], v[240:241], v[152:153], v[244:245]
	s_waitcnt vmcnt(6)
	v_pk_fma_f32 v[154:155], v[110:111], v[150:151], v[160:161] op_sel_hi:[1,0,1]
	v_pk_fma_f32 v[156:157], v[112:113], v[150:151], v[192:193] op_sel_hi:[1,0,1]
	v_pk_fma_f32 v[160:161], v[106:107], v[150:151], v[194:195] op_sel_hi:[1,0,1]
	v_pk_fma_f32 v[186:187], v[108:109], v[150:151], v[190:191] op_sel_hi:[1,0,1]
	v_pk_fma_f32 v[156:157], v[104:105], v[150:151], v[156:157] op_sel:[0,1,0]
	v_pk_fma_f32 v[154:155], v[102:103], v[150:151], v[154:155] op_sel:[0,1,0]
	v_pk_fma_f32 v[186:187], v[100:101], v[150:151], v[186:187] op_sel:[0,1,0]
	v_pk_fma_f32 v[160:161], v[98:99], v[150:151], v[160:161] op_sel:[0,1,0]
	v_cvt_pk_bf16_f32 v150, v150, v151
	v_cvt_pk_bf16_f32 v151, v152, v153
	v_pk_fma_f32 v[154:155], v[50:51], v[152:153], v[154:155] op_sel_hi:[1,0,1]
	v_pk_fma_f32 v[156:157], v[52:53], v[152:153], v[156:157] op_sel_hi:[1,0,1]
	v_pk_fma_f32 v[160:161], v[62:63], v[152:153], v[160:161] op_sel_hi:[1,0,1]
	v_pk_fma_f32 v[186:187], v[64:65], v[152:153], v[186:187] op_sel_hi:[1,0,1]
	global_store_dwordx2 v[158:159], v[150:151], off offset:1024
	v_pk_fma_f32 v[188:189], v[60:61], v[152:153], v[156:157] op_sel:[0,1,0]
	v_pk_fma_f32 v[190:191], v[58:59], v[152:153], v[154:155] op_sel:[0,1,0]
	v_pk_fma_f32 v[186:187], v[56:57], v[152:153], v[186:187] op_sel:[0,1,0]
	v_pk_fma_f32 v[160:161], v[54:55], v[152:153], v[160:161] op_sel:[0,1,0]
	ds_read_b128 v[150:153], v178 offset:3072
	ds_read_b128 v[154:157], v178 offset:19456
	s_waitcnt lgkmcnt(0)
	v_pk_fma_f32 v[146:147], v[146:147], v[150:151], v[154:155]
	s_waitcnt vmcnt(7)
	v_pk_fma_f32 v[150:151], v[126:127], v[146:147], v[190:191] op_sel_hi:[1,0,1]
	v_pk_fma_f32 v[148:149], v[148:149], v[152:153], v[156:157]
	v_pk_fma_f32 v[150:151], v[118:119], v[146:147], v[150:151] op_sel:[0,1,0]
	v_pk_fma_f32 v[152:153], v[128:129], v[146:147], v[188:189] op_sel_hi:[1,0,1]
	v_pk_fma_f32 v[154:155], v[122:123], v[146:147], v[160:161] op_sel_hi:[1,0,1]
	v_pk_fma_f32 v[156:157], v[124:125], v[146:147], v[186:187] op_sel_hi:[1,0,1]
	v_pk_fma_f32 v[150:151], v[66:67], v[148:149], v[150:151] op_sel_hi:[1,0,1]
	v_pk_fma_f32 v[152:153], v[120:121], v[146:147], v[152:153] op_sel:[0,1,0]
	v_pk_fma_f32 v[156:157], v[116:117], v[146:147], v[156:157] op_sel:[0,1,0]
	v_pk_fma_f32 v[154:155], v[114:115], v[146:147], v[154:155] op_sel:[0,1,0]
	v_pk_fma_f32 v[160:161], v[74:75], v[148:149], v[150:151] op_sel:[0,1,0]
	v_cvt_pk_bf16_f32 v146, v146, v147
	v_cvt_pk_bf16_f32 v147, v148, v149
	global_store_dwordx2 v[158:159], v[146:147], off offset:1536
	v_pk_fma_f32 v[152:153], v[68:69], v[148:149], v[152:153] op_sel_hi:[1,0,1]
	v_pk_fma_f32 v[154:155], v[78:79], v[148:149], v[154:155] op_sel_hi:[1,0,1]
	v_pk_fma_f32 v[156:157], v[80:81], v[148:149], v[156:157] op_sel_hi:[1,0,1]
	v_pk_fma_f32 v[152:153], v[76:77], v[148:149], v[152:153] op_sel:[0,1,0]
	v_pk_fma_f32 v[150:151], v[72:73], v[148:149], v[156:157] op_sel:[0,1,0]
	v_pk_fma_f32 v[154:155], v[70:71], v[148:149], v[154:155] op_sel:[0,1,0]
	s_nop 1
	v_permlane32_swap_b32 v160, v154
	v_permlane32_swap_b32 v161, v155
	v_permlane32_swap_b32 v152, v150
	v_permlane32_swap_b32 v153, v151
	v_pk_add_f32 v[160:161], v[160:161], v[154:155]
	v_pk_add_f32 v[152:153], v[152:153], v[150:151]
	s_nop 1
	v_permlane16_swap_b32 v160, v152
	v_permlane16_swap_b32 v161, v153
	v_pk_add_f32 v[160:161], v[160:161], v[152:153]
	v_add_u32_e32 v146, v176, v221
	s_nop 0
	v_add_f32_dpp v160, v160, v160 quad_perm:[1,0,3,2] row_mask:0xf bank_mask:0xf
	v_add_f32_dpp v161, v161, v161 quad_perm:[1,0,3,2] row_mask:0xf bank_mask:0xf
	s_nop 0
	v_add_f32_dpp v160, v160, v160 quad_perm:[2,3,0,1] row_mask:0xf bank_mask:0xf
	v_add_f32_dpp v161, v161, v161 quad_perm:[2,3,0,1] row_mask:0xf bank_mask:0xf
	s_nop 0
	v_add_f32_dpp v160, v160, v160 row_half_mirror row_mask:0xf bank_mask:0xf
	v_add_f32_dpp v161, v161, v161 row_half_mirror row_mask:0xf bank_mask:0xf
	s_nop 0
	v_add_f32_dpp v160, v160, v160 row_mirror row_mask:0xf bank_mask:0xf
	v_add_f32_dpp v161, v161, v161 row_mirror row_mask:0xf bank_mask:0xf
	s_and_saveexec_b64 s[0:1], s[40:41]
	global_store_dwordx2 v146, v[160:161], s[92:93]
	s_branch .LBB0_139
